# GEMM: per-K-step address update VALU interleaved among the later MFMAs instead of after them (M0 base computed in its own SGPR); DMA positions 2/6/10 and attention loops unchanged
# baseline (speedup 1.0000x reference)
; #define BAR __builtin_amdgcn_s_barrier()
;     ...
;       for (int k = 0; k < 2; ++k)
; #pragma unroll
;         for (int m = 0; m < 4; ++m)
; #pragma unroll
;           for (int n = 0; n < 4; ++n) acc[m][n] = __builtin_amdgcn_mfma_f32_16x16x32_bf16(Bf[n][k], At[m][k], acc[m][n], 0, 0, 0);
;       __builtin_amdgcn_s_setprio(0);
;       __builtin_amdgcn_sched_barrier(0);
;       BAR;
;       __builtin_amdgcn_sched_barrier(0);
;       b = (b == 2) ? 0 : b + 1;
;     }
.Lgc1_skd5:
	v_mfma_f32_16x16x32_bf16 v[20:23], v[120:123], v[100:103], v[20:23]
	v_mfma_f32_16x16x32_bf16 v[16:19], v[124:127], v[100:103], v[16:19]
	v_mfma_f32_16x16x32_bf16 v[12:15], v[112:115], v[96:99], v[12:15]
	s_add_i32 s36, s61, 1
	s_cmp_lg_u32 s61, 2
	s_cselect_b32 s61, s36, 0
	s_add_i32 s62, s62, 1
	s_add_u32 s10, s10, 0x80
	s_addc_u32 s11, s11, 0
	s_mul_i32 s36, s61, 0xc000
	s_mul_i32 s98, s61, 0x6000
	s_addk_i32 s98, 0xa000
	s_cmp_lg_u32 s61, 0
	s_cselect_b32 s98, s98, 0xc000
	s_lshl_b32 s98, s98, 1
	s_add_u32 s98, s98, s99
	v_mfma_f32_16x16x32_bf16 v[8:11], v[116:119], v[96:99], v[8:11]
	v_mfma_f32_16x16x32_bf16 v[4:7], v[120:123], v[96:99], v[4:7]
	v_add_u32_e32 v160, s36, v174
	v_mfma_f32_16x16x32_bf16 v[0:3], v[124:127], v[96:99], v[0:3]
	v_mfma_f32_16x16x32_bf16 v[60:63], v[80:83], v[76:79], v[60:63]
	v_add_u32_e32 v161, s36, v131
	v_mfma_f32_16x16x32_bf16 v[56:59], v[84:87], v[76:79], v[56:59]
	v_mfma_f32_16x16x32_bf16 v[52:55], v[88:91], v[76:79], v[52:55]
	v_lshl_add_u64 v[162:163], v[162:163], 0, s[14:15]
	v_mfma_f32_16x16x32_bf16 v[48:51], v[92:95], v[76:79], v[48:51]
	v_mfma_f32_16x16x32_bf16 v[44:47], v[80:83], v[72:75], v[44:47]
	v_lshl_add_u64 v[164:165], v[164:165], 0, s[14:15]
	v_mfma_f32_16x16x32_bf16 v[40:43], v[84:87], v[72:75], v[40:43]
	v_mfma_f32_16x16x32_bf16 v[36:39], v[88:91], v[72:75], v[36:39]
	v_lshl_add_u64 v[166:167], v[166:167], 0, s[14:15]
	v_mfma_f32_16x16x32_bf16 v[32:35], v[92:95], v[72:75], v[32:35]
	v_mfma_f32_16x16x32_bf16 v[28:31], v[80:83], v[68:71], v[28:31]
	v_lshl_add_u64 v[168:169], v[168:169], 0, s[14:15]
	v_mfma_f32_16x16x32_bf16 v[24:27], v[84:87], v[68:71], v[24:27]
	v_mfma_f32_16x16x32_bf16 v[20:23], v[88:91], v[68:71], v[20:23]
	v_lshl_add_u64 v[170:171], v[170:171], 0, s[14:15]
	v_mfma_f32_16x16x32_bf16 v[16:19], v[92:95], v[68:71], v[16:19]
	v_mfma_f32_16x16x32_bf16 v[12:15], v[80:83], v[64:67], v[12:15]
	v_lshl_add_u64 v[172:173], v[172:173], 0, s[14:15]
	v_mfma_f32_16x16x32_bf16 v[8:11], v[84:87], v[64:67], v[8:11]
	v_mfma_f32_16x16x32_bf16 v[4:7], v[88:91], v[64:67], v[4:7]
	v_mfma_f32_16x16x32_bf16 v[0:3], v[92:95], v[64:67], v[0:3]
	s_setprio 0
	s_barrier
	s_cmpk_eq_i32 s10, 0x1600
	s_cbranch_scc1 .LBB0_46

; #define BAR __builtin_amdgcn_s_barrier()
;     ...
;       for (int k = 0; k < 2; ++k)
; #pragma unroll
;         for (int m = 0; m < 4; ++m)
; #pragma unroll
;           for (int n = 0; n < 4; ++n) acc[m][n] = __builtin_amdgcn_mfma_f32_16x16x32_bf16(Bf[n][k], At[m][k], acc[m][n], 0, 0, 0);
;       __builtin_amdgcn_s_setprio(0);
;       __builtin_amdgcn_sched_barrier(0);
;       BAR;
;       __builtin_amdgcn_sched_barrier(0);
;       b = (b == 2) ? 0 : b + 1;
;     }
.Lgc2_skd5:
	v_mfma_f32_16x16x32_bf16 v[28:31], v[120:123], v[100:103], v[28:31]
	v_mfma_f32_16x16x32_bf16 v[20:23], v[124:127], v[100:103], v[20:23]
	v_mfma_f32_16x16x32_bf16 v[8:11], v[112:115], v[96:99], v[8:11]
	s_add_i32 s36, s43, 1
	s_cmp_lg_u32 s43, 2
	s_cselect_b32 s43, s36, 0
	s_add_i32 s64, s64, 1
	s_add_u32 s10, s10, 0x80
	s_addc_u32 s11, s11, 0
	s_mul_i32 s36, s43, 0xc000
	s_mul_i32 s98, s43, 0x6000
	s_addk_i32 s98, 0xa000
	s_cmp_lg_u32 s43, 0
	s_cselect_b32 s98, s98, 0xc000
	s_lshl_b32 s98, s98, 1
	s_add_u32 s98, s98, s99
	v_mfma_f32_16x16x32_bf16 v[0:3], v[116:119], v[96:99], v[0:3]
	v_mfma_f32_16x16x32_bf16 v[12:15], v[120:123], v[96:99], v[12:15]
	v_add_u32_e32 v160, s36, v174
	v_mfma_f32_16x16x32_bf16 v[4:7], v[124:127], v[96:99], v[4:7]
	v_mfma_f32_16x16x32_bf16 v[56:59], v[80:83], v[76:79], v[56:59]
	v_add_u32_e32 v161, s36, v131
	v_mfma_f32_16x16x32_bf16 v[48:51], v[84:87], v[76:79], v[48:51]
	v_mfma_f32_16x16x32_bf16 v[60:63], v[88:91], v[76:79], v[60:63]
	v_lshl_add_u64 v[162:163], v[162:163], 0, s[14:15]
	v_mfma_f32_16x16x32_bf16 v[52:55], v[92:95], v[76:79], v[52:55]
	v_mfma_f32_16x16x32_bf16 v[40:43], v[80:83], v[72:75], v[40:43]
	v_lshl_add_u64 v[164:165], v[164:165], 0, s[14:15]
	v_mfma_f32_16x16x32_bf16 v[32:35], v[84:87], v[72:75], v[32:35]
	v_mfma_f32_16x16x32_bf16 v[44:47], v[88:91], v[72:75], v[44:47]
	v_lshl_add_u64 v[166:167], v[166:167], 0, s[14:15]
	v_mfma_f32_16x16x32_bf16 v[36:39], v[92:95], v[72:75], v[36:39]
	v_mfma_f32_16x16x32_bf16 v[24:27], v[80:83], v[68:71], v[24:27]
	v_lshl_add_u64 v[168:169], v[168:169], 0, s[14:15]
	v_mfma_f32_16x16x32_bf16 v[16:19], v[84:87], v[68:71], v[16:19]
	v_mfma_f32_16x16x32_bf16 v[28:31], v[88:91], v[68:71], v[28:31]
	v_lshl_add_u64 v[170:171], v[170:171], 0, s[14:15]
	v_mfma_f32_16x16x32_bf16 v[20:23], v[92:95], v[68:71], v[20:23]
	v_mfma_f32_16x16x32_bf16 v[8:11], v[80:83], v[64:67], v[8:11]
	v_lshl_add_u64 v[172:173], v[172:173], 0, s[14:15]
	v_mfma_f32_16x16x32_bf16 v[0:3], v[84:87], v[64:67], v[0:3]
	v_mfma_f32_16x16x32_bf16 v[12:15], v[88:91], v[64:67], v[12:15]
	v_mfma_f32_16x16x32_bf16 v[4:7], v[92:95], v[64:67], v[4:7]
	s_setprio 0
	s_barrier
	s_cmpk_eq_i32 s10, 0x800
	s_cbranch_scc1 .LBB0_78

; #define BAR __builtin_amdgcn_s_barrier()
;     ...
;       for (int k = 0; k < 2; ++k)
; #pragma unroll
;         for (int m = 0; m < 4; ++m)
; #pragma unroll
;           for (int n = 0; n < 4; ++n) acc[m][n] = __builtin_amdgcn_mfma_f32_16x16x32_bf16(Bf[n][k], At[m][k], acc[m][n], 0, 0, 0);
;       __builtin_amdgcn_s_setprio(0);
;       __builtin_amdgcn_sched_barrier(0);
;       BAR;
;       __builtin_amdgcn_sched_barrier(0);
;       b = (b == 2) ? 0 : b + 1;
;     }
.Lgc3_skd5:
	v_mfma_f32_16x16x32_bf16 v[20:23], v[120:123], v[100:103], v[20:23]
	v_mfma_f32_16x16x32_bf16 v[16:19], v[124:127], v[100:103], v[16:19]
	v_mfma_f32_16x16x32_bf16 v[12:15], v[112:115], v[96:99], v[12:15]
	s_add_i32 s36, s39, 1
	s_cmp_lg_u32 s39, 2
	s_cselect_b32 s39, s36, 0
	s_add_i32 s41, s41, 1
	s_add_u32 s10, s10, 0x80
	s_addc_u32 s11, s11, 0
	s_mul_i32 s36, s39, 0xc000
	s_mul_i32 s98, s39, 0x6000
	s_addk_i32 s98, 0xa000
	s_cmp_lg_u32 s39, 0
	s_cselect_b32 s98, s98, 0xc000
	s_lshl_b32 s98, s98, 1
	s_add_u32 s98, s98, s99
	v_mfma_f32_16x16x32_bf16 v[8:11], v[116:119], v[96:99], v[8:11]
	v_mfma_f32_16x16x32_bf16 v[4:7], v[120:123], v[96:99], v[4:7]
	v_add_u32_e32 v160, s36, v174
	v_mfma_f32_16x16x32_bf16 v[0:3], v[124:127], v[96:99], v[0:3]
	v_mfma_f32_16x16x32_bf16 v[60:63], v[80:83], v[76:79], v[60:63]
	v_add_u32_e32 v161, s36, v131
	v_mfma_f32_16x16x32_bf16 v[56:59], v[84:87], v[76:79], v[56:59]
	v_mfma_f32_16x16x32_bf16 v[52:55], v[88:91], v[76:79], v[52:55]
	v_lshl_add_u64 v[162:163], v[162:163], 0, s[14:15]
	v_mfma_f32_16x16x32_bf16 v[48:51], v[92:95], v[76:79], v[48:51]
	v_mfma_f32_16x16x32_bf16 v[44:47], v[80:83], v[72:75], v[44:47]
	v_lshl_add_u64 v[164:165], v[164:165], 0, s[14:15]
	v_mfma_f32_16x16x32_bf16 v[40:43], v[84:87], v[72:75], v[40:43]
	v_mfma_f32_16x16x32_bf16 v[36:39], v[88:91], v[72:75], v[36:39]
	v_lshl_add_u64 v[166:167], v[166:167], 0, s[14:15]
	v_mfma_f32_16x16x32_bf16 v[32:35], v[92:95], v[72:75], v[32:35]
	v_mfma_f32_16x16x32_bf16 v[28:31], v[80:83], v[68:71], v[28:31]
	v_lshl_add_u64 v[168:169], v[168:169], 0, s[14:15]
	v_mfma_f32_16x16x32_bf16 v[24:27], v[84:87], v[68:71], v[24:27]
	v_mfma_f32_16x16x32_bf16 v[20:23], v[88:91], v[68:71], v[20:23]
	v_lshl_add_u64 v[170:171], v[170:171], 0, s[14:15]
	v_mfma_f32_16x16x32_bf16 v[16:19], v[92:95], v[68:71], v[16:19]
	v_mfma_f32_16x16x32_bf16 v[12:15], v[80:83], v[64:67], v[12:15]
	v_lshl_add_u64 v[172:173], v[172:173], 0, s[14:15]
	v_mfma_f32_16x16x32_bf16 v[8:11], v[84:87], v[64:67], v[8:11]
	v_mfma_f32_16x16x32_bf16 v[4:7], v[88:91], v[64:67], v[4:7]
	v_mfma_f32_16x16x32_bf16 v[0:3], v[92:95], v[64:67], v[0:3]
	s_setprio 0
	s_barrier
	s_cmpk_eq_i32 s10, 0x800
	s_cbranch_scc1 .LBB0_113

; #define BAR __builtin_amdgcn_s_barrier()
;     ...
;       for (int k = 0; k < 2; ++k)
; #pragma unroll
;         for (int m = 0; m < 4; ++m)
; #pragma unroll
;           for (int n = 0; n < 4; ++n) acc[m][n] = __builtin_amdgcn_mfma_f32_16x16x32_bf16(Bf[n][k], At[m][k], acc[m][n], 0, 0, 0);
;       __builtin_amdgcn_s_setprio(0);
;       __builtin_amdgcn_sched_barrier(0);
;       BAR;
;       __builtin_amdgcn_sched_barrier(0);
;       b = (b == 2) ? 0 : b + 1;
;     }
.Lgc4_skd5:
	v_mfma_f32_16x16x32_bf16 v[20:23], v[120:123], v[100:103], v[20:23]
	v_mfma_f32_16x16x32_bf16 v[16:19], v[124:127], v[100:103], v[16:19]
	v_mfma_f32_16x16x32_bf16 v[12:15], v[112:115], v[96:99], v[12:15]
	s_add_i32 s36, s39, 1
	s_cmp_lg_u32 s39, 2
	s_cselect_b32 s39, s36, 0
	s_add_i32 s41, s41, 1
	s_add_u32 s10, s10, 0x80
	s_addc_u32 s11, s11, 0
	s_mul_i32 s36, s39, 0xc000
	s_mul_i32 s98, s39, 0x6000
	s_addk_i32 s98, 0xa000
	s_cmp_lg_u32 s39, 0
	s_cselect_b32 s98, s98, 0xc000
	s_lshl_b32 s98, s98, 1
	s_add_u32 s98, s98, s99
	v_mfma_f32_16x16x32_bf16 v[8:11], v[116:119], v[96:99], v[8:11]
	v_mfma_f32_16x16x32_bf16 v[4:7], v[120:123], v[96:99], v[4:7]
	v_add_u32_e32 v160, s36, v174
	v_mfma_f32_16x16x32_bf16 v[0:3], v[124:127], v[96:99], v[0:3]
	v_mfma_f32_16x16x32_bf16 v[56:59], v[80:83], v[76:79], v[56:59]
	v_add_u32_e32 v161, s36, v131
	v_mfma_f32_16x16x32_bf16 v[60:63], v[84:87], v[76:79], v[60:63]
	v_mfma_f32_16x16x32_bf16 v[52:55], v[88:91], v[76:79], v[52:55]
	v_lshl_add_u64 v[162:163], v[162:163], 0, s[14:15]
	v_mfma_f32_16x16x32_bf16 v[48:51], v[92:95], v[76:79], v[48:51]
	v_mfma_f32_16x16x32_bf16 v[44:47], v[80:83], v[72:75], v[44:47]
	v_lshl_add_u64 v[164:165], v[164:165], 0, s[14:15]
	v_mfma_f32_16x16x32_bf16 v[40:43], v[84:87], v[72:75], v[40:43]
	v_mfma_f32_16x16x32_bf16 v[36:39], v[88:91], v[72:75], v[36:39]
	v_lshl_add_u64 v[166:167], v[166:167], 0, s[14:15]
	v_mfma_f32_16x16x32_bf16 v[32:35], v[92:95], v[72:75], v[32:35]
	v_mfma_f32_16x16x32_bf16 v[28:31], v[80:83], v[68:71], v[28:31]
	v_lshl_add_u64 v[168:169], v[168:169], 0, s[14:15]
	v_mfma_f32_16x16x32_bf16 v[24:27], v[84:87], v[68:71], v[24:27]
	v_mfma_f32_16x16x32_bf16 v[20:23], v[88:91], v[68:71], v[20:23]
	v_lshl_add_u64 v[170:171], v[170:171], 0, s[14:15]
	v_mfma_f32_16x16x32_bf16 v[16:19], v[92:95], v[68:71], v[16:19]
	v_mfma_f32_16x16x32_bf16 v[12:15], v[80:83], v[64:67], v[12:15]
	v_lshl_add_u64 v[172:173], v[172:173], 0, s[14:15]
	v_mfma_f32_16x16x32_bf16 v[8:11], v[84:87], v[64:67], v[8:11]
	v_mfma_f32_16x16x32_bf16 v[4:7], v[88:91], v[64:67], v[4:7]
	v_mfma_f32_16x16x32_bf16 v[0:3], v[92:95], v[64:67], v[0:3]
	s_setprio 0
	s_barrier
	s_cmpk_eq_i32 s10, 0x800
	s_cbranch_scc1 .LBB0_1026

; #define STAGE_ALL(bufi, kt) do { STAGEA(SA(bufi, 0), brow, kt); STAGEA(SA(bufi, 1), brow + HALF, kt); STAGEB(SB(bufi), bcol, kt); } while (0)
; #define WAIT_V(n) asm volatile("s_waitcnt vmcnt(" #n ")" ::: "memory")
; #define BAR __builtin_amdgcn_s_barrier()
;     ...
;       if (t + 2 < nt) { const int b2 = (b == 0) ? 2 : b - 1; STAGE_ALL(b2, t + 2); WAIT_V(6); } else { WAIT_V(0); }
;       asm volatile("s_waitcnt lgkmcnt(0)" ::: "memory");
;       __builtin_amdgcn_sched_barrier(0);
;       BAR;
;       __builtin_amdgcn_sched_barrier(0);
;       __builtin_amdgcn_s_setprio(1);
; #pragma unroll
;       for (int k = 0; k < 2; ++k)
; #pragma unroll
;         for (int m = 0; m < 4; ++m)
; #pragma unroll
;           for (int n = 0; n < 4; ++n) acc[m][n] = __builtin_amdgcn_mfma_f32_16x16x32_bf16(Bf[n][k], At[m][k], acc[m][n], 0, 0, 0);
;       __builtin_amdgcn_s_setprio(0);
;       __builtin_amdgcn_sched_barrier(0);
;       BAR;
;       __builtin_amdgcn_sched_barrier(0);
;       b = (b == 2) ? 0 : b + 1;
.Lgc5_skd5:
	v_mfma_f32_16x16x32_bf16 v[20:23], v[120:123], v[100:103], v[20:23]
	v_mfma_f32_16x16x32_bf16 v[16:19], v[124:127], v[100:103], v[16:19]
	v_mfma_f32_16x16x32_bf16 v[12:15], v[112:115], v[96:99], v[12:15]
	s_add_i32 s36, s60, 1
	s_cmp_lg_u32 s60, 2
	s_cselect_b32 s60, s36, 0
	s_add_i32 s61, s61, 1
	s_add_u32 s10, s10, 0x80
	s_addc_u32 s11, s11, 0
	s_mul_i32 s36, s60, 0xc000
	s_mul_i32 s98, s60, 0x6000
	s_addk_i32 s98, 0xa000
	s_cmp_lg_u32 s60, 0
	s_cselect_b32 s98, s98, 0xc000
	s_lshl_b32 s98, s98, 1
	s_add_u32 s98, s98, s99
	v_mfma_f32_16x16x32_bf16 v[8:11], v[116:119], v[96:99], v[8:11]
	v_mfma_f32_16x16x32_bf16 v[4:7], v[120:123], v[96:99], v[4:7]
	v_add_u32_e32 v160, s36, v174
	v_mfma_f32_16x16x32_bf16 v[0:3], v[124:127], v[96:99], v[0:3]
	v_mfma_f32_16x16x32_bf16 v[60:63], v[80:83], v[76:79], v[60:63]
	v_add_u32_e32 v161, s36, v131
	v_mfma_f32_16x16x32_bf16 v[56:59], v[84:87], v[76:79], v[56:59]
	v_mfma_f32_16x16x32_bf16 v[52:55], v[88:91], v[76:79], v[52:55]
	v_lshl_add_u64 v[162:163], v[162:163], 0, s[14:15]
	v_mfma_f32_16x16x32_bf16 v[48:51], v[92:95], v[76:79], v[48:51]
	v_mfma_f32_16x16x32_bf16 v[44:47], v[80:83], v[72:75], v[44:47]
	v_lshl_add_u64 v[164:165], v[164:165], 0, s[14:15]
	v_mfma_f32_16x16x32_bf16 v[40:43], v[84:87], v[72:75], v[40:43]
	v_mfma_f32_16x16x32_bf16 v[36:39], v[88:91], v[72:75], v[36:39]
	v_lshl_add_u64 v[166:167], v[166:167], 0, s[14:15]
	v_mfma_f32_16x16x32_bf16 v[32:35], v[92:95], v[72:75], v[32:35]
	v_mfma_f32_16x16x32_bf16 v[28:31], v[80:83], v[68:71], v[28:31]
	v_lshl_add_u64 v[168:169], v[168:169], 0, s[14:15]
	v_mfma_f32_16x16x32_bf16 v[24:27], v[84:87], v[68:71], v[24:27]
	v_mfma_f32_16x16x32_bf16 v[20:23], v[88:91], v[68:71], v[20:23]
	v_lshl_add_u64 v[170:171], v[170:171], 0, s[14:15]
	v_mfma_f32_16x16x32_bf16 v[16:19], v[92:95], v[68:71], v[16:19]
	v_mfma_f32_16x16x32_bf16 v[12:15], v[80:83], v[64:67], v[12:15]
	v_lshl_add_u64 v[172:173], v[172:173], 0, s[14:15]
	v_mfma_f32_16x16x32_bf16 v[8:11], v[84:87], v[64:67], v[8:11]
	v_mfma_f32_16x16x32_bf16 v[4:7], v[88:91], v[64:67], v[4:7]
	v_mfma_f32_16x16x32_bf16 v[0:3], v[92:95], v[64:67], v[0:3]
	s_setprio 0
	s_barrier
	s_cmpk_eq_i32 s10, 0x1600
	s_cbranch_scc1 .LBB0_1062

; #define STAGE_ALL(bufi, kt) do { STAGEA(SA(bufi, 0), brow, kt); STAGEA(SA(bufi, 1), brow + HALF, kt); STAGEB(SB(bufi), bcol, kt); } while (0)
; #define WAIT_V(n) asm volatile("s_waitcnt vmcnt(" #n ")" ::: "memory")
; #define BAR __builtin_amdgcn_s_barrier()
;     ...
;       if (t + 2 < nt) { const int b2 = (b == 0) ? 2 : b - 1; STAGE_ALL(b2, t + 2); WAIT_V(6); } else { WAIT_V(0); }
;       asm volatile("s_waitcnt lgkmcnt(0)" ::: "memory");
;       __builtin_amdgcn_sched_barrier(0);
;       BAR;
;       __builtin_amdgcn_sched_barrier(0);
;       __builtin_amdgcn_s_setprio(1);
; #pragma unroll
;       for (int k = 0; k < 2; ++k)
; #pragma unroll
;         for (int m = 0; m < 4; ++m)
; #pragma unroll
;           for (int n = 0; n < 4; ++n) acc[m][n] = __builtin_amdgcn_mfma_f32_16x16x32_bf16(Bf[n][k], At[m][k], acc[m][n], 0, 0, 0);
;       __builtin_amdgcn_s_setprio(0);
;       __builtin_amdgcn_sched_barrier(0);
;       BAR;
;       __builtin_amdgcn_sched_barrier(0);
;       b = (b == 2) ? 0 : b + 1;
.Lgc6_skd5:
	v_mfma_f32_16x16x32_bf16 v[28:31], v[120:123], v[100:103], v[28:31]
	v_mfma_f32_16x16x32_bf16 v[20:23], v[124:127], v[100:103], v[20:23]
	v_mfma_f32_16x16x32_bf16 v[8:11], v[112:115], v[96:99], v[8:11]
	s_add_i32 s36, s43, 1
	s_cmp_lg_u32 s43, 2
	s_cselect_b32 s43, s36, 0
	s_add_i32 s58, s58, 1
	s_add_u32 s10, s10, 0x80
	s_addc_u32 s11, s11, 0
	s_mul_i32 s36, s43, 0xc000
	s_mul_i32 s98, s43, 0x6000
	s_addk_i32 s98, 0xa000
	s_cmp_lg_u32 s43, 0
	s_cselect_b32 s98, s98, 0xc000
	s_lshl_b32 s98, s98, 1
	s_add_u32 s98, s98, s99
	v_mfma_f32_16x16x32_bf16 v[0:3], v[116:119], v[96:99], v[0:3]
	v_mfma_f32_16x16x32_bf16 v[12:15], v[120:123], v[96:99], v[12:15]
	v_add_u32_e32 v160, s36, v174
	v_mfma_f32_16x16x32_bf16 v[4:7], v[124:127], v[96:99], v[4:7]
	v_mfma_f32_16x16x32_bf16 v[56:59], v[80:83], v[76:79], v[56:59]
	v_add_u32_e32 v161, s36, v131
	v_mfma_f32_16x16x32_bf16 v[48:51], v[84:87], v[76:79], v[48:51]
	v_mfma_f32_16x16x32_bf16 v[60:63], v[88:91], v[76:79], v[60:63]
	v_lshl_add_u64 v[162:163], v[162:163], 0, s[14:15]
	v_mfma_f32_16x16x32_bf16 v[52:55], v[92:95], v[76:79], v[52:55]
	v_mfma_f32_16x16x32_bf16 v[40:43], v[80:83], v[72:75], v[40:43]
	v_lshl_add_u64 v[164:165], v[164:165], 0, s[14:15]
	v_mfma_f32_16x16x32_bf16 v[32:35], v[84:87], v[72:75], v[32:35]
	v_mfma_f32_16x16x32_bf16 v[44:47], v[88:91], v[72:75], v[44:47]
	v_lshl_add_u64 v[166:167], v[166:167], 0, s[14:15]
	v_mfma_f32_16x16x32_bf16 v[36:39], v[92:95], v[72:75], v[36:39]
	v_mfma_f32_16x16x32_bf16 v[24:27], v[80:83], v[68:71], v[24:27]
	v_lshl_add_u64 v[168:169], v[168:169], 0, s[14:15]
	v_mfma_f32_16x16x32_bf16 v[16:19], v[84:87], v[68:71], v[16:19]
	v_mfma_f32_16x16x32_bf16 v[28:31], v[88:91], v[68:71], v[28:31]
	v_lshl_add_u64 v[170:171], v[170:171], 0, s[14:15]
	v_mfma_f32_16x16x32_bf16 v[20:23], v[92:95], v[68:71], v[20:23]
	v_mfma_f32_16x16x32_bf16 v[8:11], v[80:83], v[64:67], v[8:11]
	v_lshl_add_u64 v[172:173], v[172:173], 0, s[14:15]
	v_mfma_f32_16x16x32_bf16 v[0:3], v[84:87], v[64:67], v[0:3]
	v_mfma_f32_16x16x32_bf16 v[12:15], v[88:91], v[64:67], v[12:15]
	v_mfma_f32_16x16x32_bf16 v[4:7], v[92:95], v[64:67], v[4:7]
	s_setprio 0
	s_barrier
	s_cmpk_eq_i32 s10, 0x800
	s_cbranch_scc1 .LBB0_1270
